# static priority raise for the younger wave half: s_setprio 1 once at kernel entry for waves 4-7 of every workgroup
# baseline (speedup 1.0000x reference)
; __global__ void __launch_bounds__(NTHREADS) mega_kernel(Params p) {
;   extern __shared__ __attribute__((aligned(16))) char lds[];
;   cg::grid_group grid = cg::this_grid();
;   unsigned bar_gen = 0;
;   for (int ph = 0; ph < NPHASE; ++ph) {
;     ...
;     const int nrep = (REPQ >= 100) ? ((ph == REPQ - 100) ? 2 : 1) : ((ph > 0 && ph < NPHASE - 1 && (ph - 1) % 14 == REPQ) ? 2 : 1);
;     ...
;     const int nrep = 1;
;     ...
;     if (ph == NPHASE - 2) continue;
;     for (int rep = 0; rep < nrep; ++rep) {
;       run_phase(p, ph, lds, rep);
_Z11mega_kernel6Params:
	s_load_dword s33, s[0:1], 0xc8
	s_add_u32 s8, s0, 0xc8
	s_load_dwordx2 s[34:35], s[0:1], 0xc0
	s_addc_u32 s9, s1, 0
	s_lshl_b32 s3, s2, 3
	s_waitcnt lgkmcnt(0)
	s_lshl_b32 s10, s33, 3
	s_cmp_eq_u32 s2, 0
	v_writelane_b32 v253, s3, 0
	s_cselect_b64 s[4:5], -1, 0
	v_writelane_b32 v253, s4, 1
	v_and_b32_e32 v129, 0x3ff, v0
	v_and_b32_e32 v1, 32, v0
	v_writelane_b32 v253, s5, 2
	s_load_dwordx4 s[4:7], s[0:1], 0xb0
	s_add_u32 s12, s34, 0x65c0000
	s_addc_u32 s13, s35, 0
	v_writelane_b32 v253, s12, 3
	v_and_b32_e32 v0, 0x3fffffff, v0
	s_load_dwordx8 s[40:47], s[0:1], 0x90
	v_writelane_b32 v253, s13, 4
	s_add_u32 s12, s34, 0x65c1800
	s_addc_u32 s13, s35, 0
	v_writelane_b32 v253, s12, 5
	s_cmp_lt_i32 s2, 4
	v_mbcnt_lo_u32_b32 v2, -1, 0
	v_writelane_b32 v253, s13, 6
	s_cselect_b64 s[12:13], -1, 0
	v_writelane_b32 v253, s12, 7
	v_mbcnt_hi_u32_b32 v188, -1, v2
	v_and_b32_e32 v2, 64, v188
	v_writelane_b32 v253, s13, 8
	s_add_u32 s12, s34, 0x65c0100
	s_addc_u32 s13, s35, 0
	v_writelane_b32 v253, s12, 9
	s_cmpk_lt_i32 s2, 0x32e0
	v_mov_b32_e32 v128, 0x358637bd
	v_writelane_b32 v253, s13, 10
	s_cselect_b64 s[12:13], -1, 0
	s_add_u32 s88, s34, 0x65c2000
	v_writelane_b32 v253, s12, 11
	s_addc_u32 s89, s35, 0
	v_mov_b32_e32 v131, 0
	v_writelane_b32 v253, s13, 12
	s_add_u32 s12, s34, 0xa5c2000
	s_addc_u32 s13, s35, 0
	v_writelane_b32 v253, s12, 13
	s_cmpk_lt_i32 s2, 0x400
	v_add_u32_e32 v189, 64, v2
	v_writelane_b32 v253, s13, 14
	s_cselect_b64 s[12:13], -1, 0
	v_writelane_b32 v253, s12, 15
	s_cmpk_lt_i32 s2, 0x1600
	v_xor_b32_e32 v190, 32, v188
	v_writelane_b32 v253, s13, 16
	s_cselect_b64 s[12:13], -1, 0
	v_writelane_b32 v253, s12, 17
	v_xor_b32_e32 v191, 16, v188
	v_xor_b32_e32 v192, 8, v188
	v_writelane_b32 v253, s13, 18
	s_add_u32 s12, s34, 0x18594000
	s_addc_u32 s13, s35, 0
	v_writelane_b32 v253, s12, 19
	v_xor_b32_e32 v193, 4, v188
	v_xor_b32_e32 v194, 2, v188
	v_writelane_b32 v253, s13, 20
	s_add_u32 s12, s34, 0x16d14000
	s_addc_u32 s13, s35, 0
	v_writelane_b32 v253, s12, 21
	v_xor_b32_e32 v195, 1, v188
	v_mov_b32_e32 v196, 0x80
	v_writelane_b32 v253, s13, 22
	s_add_u32 s12, s34, 0x16d94000
	s_addc_u32 s13, s35, 0
	v_writelane_b32 v253, s12, 23
	v_mov_b32_e32 v197, 0x1000
	v_mov_b32_e32 v198, 0x800
	v_writelane_b32 v253, s13, 24
	s_add_u32 s12, s34, 0xf5c4000
	s_addc_u32 s13, s35, 0
	v_writelane_b32 v253, s12, 25
	v_mov_b32_e32 v199, 0xff800000
	v_mov_b32_e32 v200, 31
	v_writelane_b32 v253, s13, 26
	s_add_u32 s12, s34, 0xfdc4000
	s_addc_u32 s13, s35, 0
	v_writelane_b32 v253, s12, 27
	v_mov_b32_e32 v201, 6
	v_mov_b32_e32 v202, 7
	v_writelane_b32 v253, s13, 28
	s_add_u32 s12, s34, 0x165c4008
	s_addc_u32 s13, s35, 0
	v_writelane_b32 v253, s12, 29
	v_mov_b32_e32 v203, 3
	v_mov_b32_e32 v204, 2
	v_writelane_b32 v253, s13, 30
	s_add_u32 s12, s34, 0x105c4000
	s_addc_u32 s13, s35, 0
	v_writelane_b32 v253, s12, 31
	v_mov_b32_e32 v205, 0x80000
	v_mov_b32_e32 v206, 15
	v_writelane_b32 v253, s13, 32
	s_add_u32 s12, s34, 0x10dc4000
	s_addc_u32 s13, s35, 0
	v_writelane_b32 v253, s12, 33
	v_mov_b32_e32 v207, 5
	v_mov_b32_e32 v208, 0xfc1
	v_writelane_b32 v253, s13, 34
	s_add_u32 s12, s34, 0x16c84000
	s_addc_u32 s13, s35, 0
	v_writelane_b32 v253, s12, 35
	v_mov_b32_e32 v209, 12
	v_mov_b32_e32 v210, 0xfffff880
	v_writelane_b32 v253, s13, 36
	s_add_u32 s12, s34, 0x16c04000
	s_addc_u32 s13, s35, 0
	v_writelane_b32 v253, s12, 37
	v_mov_b32_e32 v211, 0xfffffb80
	v_mov_b32_e32 v212, 0x10dc4000
	v_writelane_b32 v253, s13, 38
	s_add_u32 s12, s34, 0x165c4000
	s_addc_u32 s13, s35, 0
	v_writelane_b32 v253, s12, 39
	v_mov_b32_e32 v213, 0x105c4000
	v_mov_b32_e32 v214, 0x280
	v_writelane_b32 v253, s13, 40
	s_add_u32 s12, s34, 0x16804000
	s_addc_u32 s13, s35, 0
	v_writelane_b32 v253, s12, 41
	s_cmp_lt_i32 s2, 64
	v_mov_b32_e32 v215, 0x300
	v_writelane_b32 v253, s13, 42
	s_cselect_b64 s[12:13], -1, 0
	v_writelane_b32 v253, s12, 43
	v_mov_b32_e32 v216, 0x380
	s_mov_b32 s53, 0x8000
	v_writelane_b32 v253, s13, 44
	s_add_u32 s12, s34, 0xbdc2000
	s_addc_u32 s13, s35, 0
	v_writelane_b32 v253, s12, 45
	s_movk_i32 s84, 0x801
	s_movk_i32 s85, 0x200
	v_writelane_b32 v253, s13, 46
	s_add_u32 s12, s34, 0x16d04000
	s_addc_u32 s13, s35, 0
	v_writelane_b32 v253, s12, 47
	s_mov_b64 s[80:81], 0x1000
	s_mov_b32 s30, 0x3a800000
	v_writelane_b32 v253, s13, 48
	s_add_u32 s12, s34, 0x115c4000
	s_addc_u32 s13, s35, 0
	v_writelane_b32 v253, s12, 49
	s_mov_b64 s[92:93], 0x80
	s_mov_b64 s[74:75], 0xa5c2180
	v_writelane_b32 v253, s13, 50
	s_add_u32 s12, s34, 0x125c4000
	s_addc_u32 s13, s35, 0
	v_writelane_b32 v253, s12, 51
	s_add_u32 s3, s34, 0xe5c2000
	s_mov_b64 s[78:79], 0x100
	v_writelane_b32 v253, s13, 52
	v_writelane_b32 v253, s3, 53
	s_addc_u32 s3, s35, 0
	s_cmpk_lt_i32 s2, 0x80
	v_writelane_b32 v253, s3, 54
	s_cselect_b64 s[12:13], -1, 0
	v_writelane_b32 v253, s12, 55
	s_add_u32 s3, s34, 0x65c0040
	s_mov_b64 s[72:73], 0x180
	v_writelane_b32 v253, s13, 56
	v_writelane_b32 v253, s3, 57
	s_addc_u32 s3, s35, 0
	s_add_u32 s12, s34, 0xcdc2000
	v_writelane_b32 v253, s3, 58
	s_addc_u32 s13, s35, 0
	v_writelane_b32 v253, s12, 59
	s_mov_b64 s[28:29], 0x280
	s_mov_b64 s[76:77], 0x300
	v_writelane_b32 v253, s13, 60
	s_add_u32 s12, s34, 0x135c4000
	s_addc_u32 s13, s35, 0
	v_writelane_b32 v253, s12, 61
	s_mov_b64 s[82:83], 0x680
	s_mov_b64 s[94:95], 0x700
	v_writelane_b32 v253, s13, 62
	s_add_u32 s12, s34, 0x14dc4000
	s_addc_u32 s13, s35, 0
	v_writelane_b32 v253, s12, 63
	s_cmpk_lt_i32 s2, 0xc80
	s_mov_b64 s[90:91], 0x780
	v_writelane_b32 v254, s13, 0
	s_load_dwordx16 s[12:27], s[0:1], 0x0
	v_writelane_b32 v254, s2, 1
	s_cselect_b64 s[2:3], -1, 0
	v_writelane_b32 v254, s2, 2
	s_mov_b64 s[96:97], 0x65c2100
	s_mov_b64 s[86:87], 0x2740100
	v_writelane_b32 v254, s3, 3
	s_waitcnt lgkmcnt(0)
; __global__ void __launch_bounds__(NTHREADS) mega_kernel(Params p) {
;   extern __shared__ __attribute__((aligned(16))) char lds[];
;   cg::grid_group grid = cg::this_grid();
;   unsigned bar_gen = 0;
;   for (int ph = 0; ph < NPHASE; ++ph) {
;     ...
;     const int nrep = (REPQ >= 100) ? ((ph == REPQ - 100) ? 2 : 1) : ((ph > 0 && ph < NPHASE - 1 && (ph - 1) % 14 == REPQ) ? 2 : 1);
;     ...
;     const int nrep = 1;
;     ...
;     if (ph == NPHASE - 2) continue;
;     for (int rep = 0; rep < nrep; ++rep) {
;       run_phase(p, ph, lds, rep);
	s_add_u32 s2, s16, 0x1000
	v_writelane_b32 v254, s12, 4
	s_addc_u32 s3, s17, 0
	s_mov_b32 s52, 0
	v_writelane_b32 v254, s13, 5
	v_writelane_b32 v254, s14, 6
	v_writelane_b32 v254, s15, 7
	v_writelane_b32 v254, s16, 8
	v_writelane_b32 v254, s17, 9
	v_writelane_b32 v254, s18, 10
	v_writelane_b32 v254, s19, 11
	v_writelane_b32 v254, s20, 12
	v_writelane_b32 v254, s21, 13
	v_writelane_b32 v254, s22, 14
	v_writelane_b32 v254, s23, 15
	v_writelane_b32 v254, s24, 16
	v_writelane_b32 v254, s25, 17
	v_writelane_b32 v254, s26, 18
	v_writelane_b32 v254, s27, 19
	v_writelane_b32 v254, s2, 20
	s_movk_i32 s20, 0x201
	s_mov_b32 s21, 0
	v_writelane_b32 v254, s3, 21
	s_add_u32 s2, s34, 0x16a04000
	s_addc_u32 s3, s35, 0
	v_writelane_b32 v254, s2, 22
	v_cmp_eq_u32_e64 s[12:13], 0, v1
	s_mov_b64 s[16:17], 0x65c2180
	v_writelane_b32 v254, s3, 23
	s_add_u32 s2, s34, 0xedc3000
	v_writelane_b32 v254, s2, 24
	s_addc_u32 s2, s35, 0
	v_writelane_b32 v254, s2, 25
	s_add_u32 s2, s6, 0xc00
	v_writelane_b32 v254, s4, 26
	s_addc_u32 s3, s7, 0
	s_ashr_i32 s11, s10, 31
	v_writelane_b32 v254, s5, 27
	v_writelane_b32 v254, s6, 28
	v_writelane_b32 v254, s7, 29
	v_writelane_b32 v254, s2, 30
	s_lshl_b64 s[36:37], s[10:11], 12
	v_writelane_b32 v252, s10, 0
	v_writelane_b32 v254, s3, 31
	s_add_i32 s2, 0, 0x1000
	v_writelane_b32 v254, s2, 32
	s_mov_b32 s2, 0
	v_writelane_b32 v254, s2, 33
	v_cmp_eq_u32_e64 s[2:3], 0, v0
	v_writelane_b32 v252, s11, 1
	s_movk_i32 s6, 0x1600
	v_writelane_b32 v254, s2, 34
	s_mov_b32 s5, 0xff800000
	s_movk_i32 s7, 0x81
	v_writelane_b32 v254, s3, 35
	v_cmp_eq_u32_e64 s[2:3], 0, v129
	s_mov_b64 s[18:19], 0x2740180
	v_writelane_b32 v252, s36, 2
	v_writelane_b32 v254, s2, 36
	s_nop 0
	v_writelane_b32 v252, s37, 3
	v_writelane_b32 v254, s3, 37
	v_writelane_b32 v254, s40, 38
	s_mov_b64 s[2:3], 0xa5c2100
	s_nop 0
	v_writelane_b32 v254, s41, 39
	v_writelane_b32 v254, s42, 40
	v_writelane_b32 v254, s43, 41
	v_writelane_b32 v254, s44, 42
	v_writelane_b32 v254, s45, 43
	v_writelane_b32 v254, s46, 44
	v_writelane_b32 v254, s47, 45
	v_writelane_b32 v254, s0, 46
	s_load_dwordx16 s[56:71], s[0:1], 0x50
	s_nop 0
	v_writelane_b32 v254, s1, 47
	s_mov_b64 s[0:1], s[8:9]
	s_waitcnt lgkmcnt(0)
	v_writelane_b32 v254, s56, 48
	s_nop 1
	v_writelane_b32 v254, s57, 49
	v_writelane_b32 v254, s58, 50
	v_writelane_b32 v254, s59, 51
	v_writelane_b32 v254, s60, 52
	v_writelane_b32 v254, s61, 53
	v_writelane_b32 v254, s62, 54
	v_writelane_b32 v254, s63, 55
	v_writelane_b32 v254, s64, 56
	v_writelane_b32 v254, s65, 57
	v_writelane_b32 v254, s66, 58
	v_writelane_b32 v254, s67, 59
	v_writelane_b32 v254, s68, 60
	v_writelane_b32 v254, s69, 61
	v_writelane_b32 v254, s70, 62
	v_writelane_b32 v254, s71, 63
	v_cmp_lt_u32_e32 vcc, 0xff, v129
	s_cbranch_vccz .Lprio_skip
	s_setprio 1
.Lprio_skip:
	s_branch .LBB0_3
.LBB0_1:
	v_readlane_b32 s36, v252, 2
	v_writelane_b32 v254, s4, 33
	v_readlane_b32 s10, v252, 0
	v_readlane_b32 s37, v252, 3
	v_readlane_b32 s11, v252, 1

; DI void grid_barrier(unsigned* ctr, unsigned target) {
;   __syncthreads();
;   if (threadIdx.x == 0) {
;     __threadfence();
;     __hip_atomic_fetch_add(ctr, 1u, __ATOMIC_RELAXED, __HIP_MEMORY_SCOPE_AGENT);
;     unsigned spins = 0;
;     while (__hip_atomic_load(ctr, __ATOMIC_RELAXED, __HIP_MEMORY_SCOPE_AGENT) < target && spins < (1u << 26)) { __builtin_amdgcn_s_sleep(2); ++spins; }
;     __threadfence();
;   }
;   __syncthreads();
; }
.Lg3_okb:
.Lg3_done:
	buffer_inv sc1
.Lg3_fin:
.LBB0_879:
	s_or_b64 exec, exec, s[8:9]
	s_mov_b64 s[10:11], -1
	s_barrier
